# NSA tile loops: rescale-needed branch tests old max vs new max right after the max, instead of the exp result vs 1.0 (shorter serial chain before the branch)
# speedup vs baseline: 1.0001x; 1.0001x over previous
; __device__ __forceinline__ void wave_lds_sync() { asm volatile("s_waitcnt lgkmcnt(0)" ::: "memory"); }
; __device__ __forceinline__ int crow(int r, int hi) { return (r & 3) + 8 * (r >> 2) + 4 * hi; }
; __device__ __forceinline__ void nsa_softmax_pv(NsaSm& st, f32x16& p0, f32x16& p1, const LAS unsigned char* vslot, LAS float* wsf, int lane, int r32, int hi, bool on = true) {
;     const float rmx = rowmax32(p0, p1); const float rm = on ? rmx : SNEG; const float mn = fmaxf(st.m, rm); const float f = __builtin_amdgcn_exp2f(st.m - mn); st.m = mn;
;     const float cs = on ? mn : 1.0e30f;
;     float s = 0.f;
; #pragma unroll
;     for (int r = 0; r < 16; ++r) { p0[r] = __builtin_amdgcn_exp2f(p0[r] - cs); p1[r] = __builtin_amdgcn_exp2f(p1[r] - cs); s += p0[r] + p1[r]; }
;     st.l = st.l * f + s;
;     if (__any(f != 1.0f)) { wave_lds_sync(); if (hi == 0) wsf[r32] = f; wave_lds_sync();
; #pragma unroll
;         for (int r = 0; r < 16; ++r) { const float fr = wsf[crow(r, hi)]; st.o0[r] *= fr; st.o1[r] *= fr; } }
.LBB0_1329:
	v_max_f32_e32 v0, v81, v81
	v_max_f32_e32 v2, v80, v80
	v_max_f32_e32 v0, v2, v0
	v_max3_f32 v2, v82, v83, v129
	v_max3_f32 v0, v0, v128, v130
	v_max3_f32 v0, v0, v131, v84
	v_max3_f32 v2, v2, v86, v87
	v_max3_f32 v0, v0, v85, v132
	v_max3_f32 v2, v2, v134, v135
	v_max3_f32 v0, v0, v133, v88
	v_max3_f32 v2, v2, v90, v91
	v_max3_f32 v0, v0, v89, v136
	v_max3_f32 v2, v2, v138, v139
	v_max3_f32 v0, v0, v137, v92
	v_max3_f32 v2, v2, v94, v95
	v_max3_f32 v0, v0, v93, v140
	v_max3_f32 v2, v2, v142, v143
	v_max3_f32 v0, v0, v141, v2
	v_mov_b32_e32 v2, v0
	s_nop 1
	v_permlane32_swap_b32_e32 v0, v2
	v_max_f32_e32 v2, v2, v2
	v_max_f32_e32 v0, v0, v0
	v_max_f32_e32 v0, v0, v2
	v_cndmask_b32_e64 v0, v248, v0, s[16:17]
	v_max_f32_e32 v2, v158, v158
	v_max_f32_e32 v0, v2, v0
	v_cmp_neq_f32_e32 vcc, v158, v0
	v_sub_f32_e32 v2, v158, v0
	v_exp_f32_e32 v6, v2
	s_cbranch_vccz .LBB0_1333
	s_waitcnt lgkmcnt(0)
	s_and_saveexec_b64 s[2:3], s[40:41]
	ds_write_b32 v246, v6
	s_or_b64 exec, exec, s[2:3]
	s_waitcnt lgkmcnt(0)
	ds_read_b128 v[2:5], v239 offset:96
	ds_read_b128 v[8:11], v239 offset:64
	ds_read_b128 v[12:15], v239 offset:32
	ds_read_b128 v[96:99], v239
	s_waitcnt lgkmcnt(3)
	v_pk_mul_f32 v[76:77], v[76:77], v[2:3]
	s_waitcnt lgkmcnt(2)
	v_pk_mul_f32 v[72:73], v[72:73], v[8:9]
	s_waitcnt lgkmcnt(1)
	v_pk_mul_f32 v[68:69], v[68:69], v[12:13]
	v_pk_mul_f32 v[78:79], v[78:79], v[4:5]
	v_pk_mul_f32 v[74:75], v[74:75], v[10:11]
	v_pk_mul_f32 v[70:71], v[70:71], v[14:15]
	s_waitcnt lgkmcnt(0)
	v_pk_mul_f32 v[66:67], v[66:67], v[98:99]
	v_pk_mul_f32 v[64:65], v[64:65], v[96:97]
	v_pk_mul_f32 v[60:61], v[60:61], v[2:3]
	v_pk_mul_f32 v[56:57], v[56:57], v[8:9]
	v_pk_mul_f32 v[52:53], v[52:53], v[12:13]
	v_pk_mul_f32 v[62:63], v[62:63], v[4:5]
	v_pk_mul_f32 v[58:59], v[58:59], v[10:11]
	v_pk_mul_f32 v[54:55], v[54:55], v[14:15]
	v_pk_mul_f32 v[50:51], v[50:51], v[98:99]
	v_pk_mul_f32 v[48:49], v[48:49], v[96:97]

; __device__ __forceinline__ void wave_lds_sync() { asm volatile("s_waitcnt lgkmcnt(0)" ::: "memory"); }
; __device__ __forceinline__ int crow(int r, int hi) { return (r & 3) + 8 * (r >> 2) + 4 * hi; }
; __device__ __forceinline__ void nsa_softmax_pv(NsaSm& st, f32x16& p0, f32x16& p1, const LAS unsigned char* vslot, LAS float* wsf, int lane, int r32, int hi, bool on = true) {
;     const float rmx = rowmax32(p0, p1); const float rm = on ? rmx : SNEG; const float mn = fmaxf(st.m, rm); const float f = __builtin_amdgcn_exp2f(st.m - mn); st.m = mn;
;     const float cs = on ? mn : 1.0e30f;
;     float s = 0.f;
; #pragma unroll
;     for (int r = 0; r < 16; ++r) { p0[r] = __builtin_amdgcn_exp2f(p0[r] - cs); p1[r] = __builtin_amdgcn_exp2f(p1[r] - cs); s += p0[r] + p1[r]; }
;     st.l = st.l * f + s;
;     if (__any(f != 1.0f)) { wave_lds_sync(); if (hi == 0) wsf[r32] = f; wave_lds_sync();
; #pragma unroll
;         for (int r = 0; r < 16; ++r) { const float fr = wsf[crow(r, hi)]; st.o0[r] *= fr; st.o1[r] *= fr; } }
.LBB0_1346:
	v_max_f32_e32 v0, v129, v129
	v_max_f32_e32 v2, v128, v128
	v_max_f32_e32 v0, v2, v0
	v_max3_f32 v2, v130, v131, v113
	v_max3_f32 v0, v0, v112, v114
	v_max3_f32 v0, v0, v115, v132
	v_max3_f32 v2, v2, v134, v135
	v_max3_f32 v0, v0, v133, v116
	v_max3_f32 v2, v2, v118, v119
	v_max3_f32 v0, v0, v117, v136
	v_max3_f32 v2, v2, v138, v139
	v_max3_f32 v0, v0, v137, v120
	v_max3_f32 v2, v2, v122, v123
	v_max3_f32 v0, v0, v121, v140
	v_max3_f32 v2, v2, v142, v143
	v_max3_f32 v0, v0, v141, v124
	v_max3_f32 v2, v2, v126, v127
	v_max3_f32 v0, v0, v125, v2
	v_mov_b32_e32 v2, v0
	s_nop 1
	v_permlane32_swap_b32_e32 v0, v2
	v_max3_f32 v0, v233, v0, v2
	v_cmp_neq_f32_e32 vcc, v233, v0
	v_sub_f32_e32 v2, v233, v0
	v_exp_f32_e32 v2, v2
	s_cbranch_vccz .LBB0_1350
	s_waitcnt lgkmcnt(0)
	s_and_saveexec_b64 s[8:9], s[40:41]
	ds_write_b32 v246, v2
	s_or_b64 exec, exec, s[8:9]
	s_waitcnt lgkmcnt(0)
	ds_read_b128 v[4:7], v239 offset:96
	ds_read_b128 v[8:11], v239 offset:64
	ds_read_b128 v[12:15], v239 offset:32
	ds_read_b128 v[144:147], v239
	s_waitcnt lgkmcnt(3)
	v_pk_mul_f32 v[108:109], v[108:109], v[4:5]
	s_waitcnt lgkmcnt(2)
	v_pk_mul_f32 v[104:105], v[104:105], v[8:9]
	s_waitcnt lgkmcnt(1)
	v_pk_mul_f32 v[100:101], v[100:101], v[12:13]
	v_pk_mul_f32 v[110:111], v[110:111], v[6:7]
	v_pk_mul_f32 v[106:107], v[106:107], v[10:11]
	v_pk_mul_f32 v[102:103], v[102:103], v[14:15]
	s_waitcnt lgkmcnt(0)
	v_pk_mul_f32 v[98:99], v[98:99], v[146:147]
	v_pk_mul_f32 v[96:97], v[96:97], v[144:145]
	v_pk_mul_f32 v[92:93], v[92:93], v[4:5]
	v_pk_mul_f32 v[88:89], v[88:89], v[8:9]
	v_pk_mul_f32 v[84:85], v[84:85], v[12:13]
	v_pk_mul_f32 v[94:95], v[94:95], v[6:7]
	v_pk_mul_f32 v[90:91], v[90:91], v[10:11]
	v_pk_mul_f32 v[86:87], v[86:87], v[14:15]
	v_pk_mul_f32 v[82:83], v[82:83], v[146:147]
	v_pk_mul_f32 v[80:81], v[80:81], v[144:145]
